# FFF1 (ff1) epilogue: HID stores coalesced via ds_bpermute + deferred, and written through (sc1); sattn cache loads prefetched
# speedup vs baseline: 1.0990x; 1.0089x over previous
.LBB0_732:
	s_mov_b64 s[12:13], s[0:1]
	s_add_i32 s4, s81, 0xfffffd7a
	s_add_i32 s10, s4, s75
	s_load_dwordx4 s[28:31], s[12:13], 0x10
	s_load_dwordx2 s[22:23], s[12:13], 0x40
	s_load_dwordx4 s[24:27], s[12:13], 0xc8
	s_ashr_i32 s11, s10, 31
	s_lshl_b64 s[10:11], s[10:11], 16
	s_waitcnt lgkmcnt(0)
	s_add_u32 s12, s28, s10
	s_waitcnt vmcnt(5)
	v_mov_b32_e32 v8, v236
	s_addc_u32 s13, s29, s11
	s_add_u32 s16, s30, s10
	v_ashrrev_i32_e32 v9, 31, v8
	s_addc_u32 s17, s31, s11
	v_lshlrev_b64 v[4:5], 4, v[8:9]
	s_waitcnt vmcnt(4)
	v_lshl_add_u64 v[12:13], s[12:13], 0, v[4:5]
	v_lshl_add_u64 v[10:11], s[16:17], 0, v[4:5]
	global_load_dwordx4 v[116:119], v[12:13], off nt
	global_load_dwordx4 v[120:123], v[10:11], off nt
	v_add_co_u32_e32 v200, vcc, 0x2000, v12
	s_nop 1
	v_addc_co_u32_e32 v201, vcc, 0, v13, vcc
	v_add_co_u32_e32 v202, vcc, 0x2000, v10
	s_nop 1
	v_addc_co_u32_e32 v203, vcc, 0, v11, vcc
	global_load_dwordx4 v[124:127], v[200:201], off nt
	global_load_dwordx4 v[128:131], v[202:203], off nt
	v_add_co_u32_e32 v200, vcc, 0x4000, v12
	s_nop 1
	v_addc_co_u32_e32 v201, vcc, 0, v13, vcc
	v_add_co_u32_e32 v202, vcc, 0x4000, v10
	s_nop 1
	v_addc_co_u32_e32 v203, vcc, 0, v11, vcc
	global_load_dwordx4 v[132:135], v[200:201], off nt
	global_load_dwordx4 v[136:139], v[202:203], off nt
	v_add_co_u32_e32 v200, vcc, 0x6000, v12
	s_nop 1
	v_addc_co_u32_e32 v201, vcc, 0, v13, vcc
	v_add_co_u32_e32 v202, vcc, 0x6000, v10
	s_nop 1
	v_addc_co_u32_e32 v203, vcc, 0, v11, vcc
	global_load_dwordx4 v[140:143], v[200:201], off nt
	global_load_dwordx4 v[144:147], v[202:203], off nt
	v_add_co_u32_e32 v200, vcc, 0x8000, v12
	s_nop 1
	v_addc_co_u32_e32 v201, vcc, 0, v13, vcc
	v_add_co_u32_e32 v202, vcc, 0x8000, v10
	s_nop 1
	v_addc_co_u32_e32 v203, vcc, 0, v11, vcc
	global_load_dwordx4 v[148:151], v[200:201], off nt
	global_load_dwordx4 v[152:155], v[202:203], off nt
	v_add_co_u32_e32 v200, vcc, 0xa000, v12
	s_nop 1
	v_addc_co_u32_e32 v201, vcc, 0, v13, vcc
	v_add_co_u32_e32 v202, vcc, 0xa000, v10
	s_nop 1
	v_addc_co_u32_e32 v203, vcc, 0, v11, vcc
	global_load_dwordx4 v[156:159], v[200:201], off nt
	global_load_dwordx4 v[160:163], v[202:203], off nt
	v_add_co_u32_e32 v200, vcc, 0xc000, v12
	s_nop 1
	v_addc_co_u32_e32 v201, vcc, 0, v13, vcc
	v_add_co_u32_e32 v202, vcc, 0xc000, v10
	s_nop 1
	v_addc_co_u32_e32 v203, vcc, 0, v11, vcc
	global_load_dwordx4 v[184:187], v[200:201], off nt
	global_load_dwordx4 v[188:191], v[202:203], off nt
	v_add_co_u32_e32 v200, vcc, 0xe000, v12
	s_nop 1
	v_addc_co_u32_e32 v201, vcc, 0, v13, vcc
	v_add_co_u32_e32 v202, vcc, 0xe000, v10
	s_nop 1
	v_addc_co_u32_e32 v203, vcc, 0, v11, vcc
	global_load_dwordx4 v[192:195], v[200:201], off nt
	global_load_dwordx4 v[196:199], v[202:203], off nt
	s_add_u32 s10, s24, s10
	s_addc_u32 s11, s25, s11
	v_lshlrev_b32_e32 v14, 4, v8
	s_add_u32 s24, s10, 0x41a6000
	s_waitcnt vmcnt(19)
	v_ashrrev_i32_e32 v16, 5, v8
	v_and_b32_e32 v15, 0x1f0, v14
	s_addc_u32 s25, s11, 0
	s_waitcnt vmcnt(16)
	v_mul_lo_u32 v17, v16, s72
	v_add_u32_e32 v14, 0, v15
	v_readlane_b32 s12, v255, 52
	s_add_u32 s28, s10, 0x51a6000
	v_readfirstlane_b32 s16, v8
	v_add_u32_e32 v15, s12, v15
	v_add_u32_e32 v18, v14, v17
	s_addc_u32 s29, s11, 0
	v_cmp_lt_i32_e32 vcc, 0, v16
	v_add_u32_e32 v17, v15, v17
	s_waitcnt vmcnt(15)
	ds_write_b128 v18, v[116:119]
	s_waitcnt vmcnt(14)
	ds_write_b128 v17, v[120:123]
	s_and_saveexec_b64 s[10:11], vcc
	s_cbranch_execz .LBB0_734
	v_subrev_u32_e32 v174, 32, v8
	v_lshlrev_b64 v[16:17], 4, v[174:175]
	v_lshl_add_u64 v[18:19], s[24:25], 0, v[16:17]
	v_lshl_add_u64 v[16:17], s[28:29], 0, v[16:17]
	global_store_dwordx4 v[18:19], v[116:119], off nt
	global_store_dwordx4 v[16:17], v[120:123], off nt
.LBB0_734:
	s_or_b64 exec, exec, s[10:11]
	v_add_u32_e32 v0, 0x200, v8
	v_ashrrev_i32_e32 v16, 5, v0
	v_add_co_u32_e32 v0, vcc, 0x2000, v12
	v_mul_lo_u32 v17, v16, s72
	s_nop 0
	v_addc_co_u32_e32 v1, vcc, 0, v13, vcc
	v_add_co_u32_e32 v4, vcc, 0x2000, v10
	s_nop 0
	v_addc_co_u32_e32 v5, vcc, 0, v11, vcc
	v_add_u32_e32 v18, v14, v17
	v_add_u32_e32 v17, v15, v17
	v_cmp_lt_i32_e32 vcc, 0, v16
	s_waitcnt vmcnt(15)
	ds_write_b128 v18, v[124:127]
	s_waitcnt vmcnt(14)
	ds_write_b128 v17, v[128:131]
	s_and_saveexec_b64 s[10:11], vcc
	s_cbranch_execz .LBB0_736
	v_mov_b64_e32 v[16:17], 0x1e00
	v_lshl_add_u64 v[16:17], v[8:9], 4, v[16:17]
	v_lshl_add_u64 v[18:19], s[24:25], 0, v[16:17]
	v_lshl_add_u64 v[16:17], s[28:29], 0, v[16:17]
	global_store_dwordx4 v[18:19], v[124:127], off nt
	global_store_dwordx4 v[16:17], v[128:131], off nt
.LBB0_736:
	s_or_b64 exec, exec, s[10:11]
	v_add_u32_e32 v0, 0x400, v8
	v_ashrrev_i32_e32 v16, 5, v0
	v_add_co_u32_e32 v0, vcc, 0x4000, v12
	v_mul_lo_u32 v17, v16, s72
	s_nop 0
	v_addc_co_u32_e32 v1, vcc, 0, v13, vcc
	v_add_co_u32_e32 v4, vcc, 0x4000, v10
	s_nop 0
	v_addc_co_u32_e32 v5, vcc, 0, v11, vcc
	v_add_u32_e32 v18, v14, v17
	v_add_u32_e32 v17, v15, v17
	v_cmp_lt_i32_e32 vcc, 0, v16
	s_waitcnt vmcnt(15)
	ds_write_b128 v18, v[132:135]
	s_waitcnt vmcnt(14)
	ds_write_b128 v17, v[136:139]
	s_and_saveexec_b64 s[10:11], vcc
	s_cbranch_execz .LBB0_738
	v_mov_b64_e32 v[16:17], 0x3e00
	v_lshl_add_u64 v[16:17], v[8:9], 4, v[16:17]
	v_lshl_add_u64 v[18:19], s[24:25], 0, v[16:17]
	v_lshl_add_u64 v[16:17], s[28:29], 0, v[16:17]
	global_store_dwordx4 v[18:19], v[132:135], off nt
	global_store_dwordx4 v[16:17], v[136:139], off nt
.LBB0_738:
	s_or_b64 exec, exec, s[10:11]
	v_add_u32_e32 v0, 0x600, v8
	v_ashrrev_i32_e32 v16, 5, v0
	v_add_co_u32_e32 v0, vcc, 0x6000, v12
	v_mul_lo_u32 v17, v16, s72
	s_nop 0
	v_addc_co_u32_e32 v1, vcc, 0, v13, vcc
	v_add_co_u32_e32 v4, vcc, 0x6000, v10
	s_nop 0
	v_addc_co_u32_e32 v5, vcc, 0, v11, vcc
	v_add_u32_e32 v18, v14, v17
	v_add_u32_e32 v17, v15, v17
	v_cmp_lt_i32_e32 vcc, 0, v16
	s_waitcnt vmcnt(15)
	ds_write_b128 v18, v[140:143]
	s_waitcnt vmcnt(14)
	ds_write_b128 v17, v[144:147]
	s_and_saveexec_b64 s[10:11], vcc
	s_cbranch_execz .LBB0_740
	v_mov_b64_e32 v[16:17], 0x5e00
	v_lshl_add_u64 v[16:17], v[8:9], 4, v[16:17]
	v_lshl_add_u64 v[18:19], s[24:25], 0, v[16:17]
	v_lshl_add_u64 v[16:17], s[28:29], 0, v[16:17]
	global_store_dwordx4 v[18:19], v[140:143], off nt
	global_store_dwordx4 v[16:17], v[144:147], off nt
.LBB0_740:
	s_or_b64 exec, exec, s[10:11]
	v_add_u32_e32 v0, 0x800, v8
	v_ashrrev_i32_e32 v16, 5, v0
	v_add_co_u32_e32 v0, vcc, 0x8000, v12
	v_mul_lo_u32 v17, v16, s72
	s_nop 0
	v_addc_co_u32_e32 v1, vcc, 0, v13, vcc
	v_add_co_u32_e32 v4, vcc, 0x8000, v10
	s_nop 0
	v_addc_co_u32_e32 v5, vcc, 0, v11, vcc
	v_add_u32_e32 v18, v14, v17
	v_add_u32_e32 v17, v15, v17
	v_cmp_lt_i32_e32 vcc, 0, v16
	s_waitcnt vmcnt(15)
	ds_write_b128 v18, v[148:151]
	s_waitcnt vmcnt(14)
	ds_write_b128 v17, v[152:155]
	s_and_saveexec_b64 s[10:11], vcc
	s_cbranch_execz .LBB0_742
	v_mov_b64_e32 v[16:17], 0x7e00
	v_lshl_add_u64 v[16:17], v[8:9], 4, v[16:17]
	v_lshl_add_u64 v[18:19], s[24:25], 0, v[16:17]
	v_lshl_add_u64 v[16:17], s[28:29], 0, v[16:17]
	global_store_dwordx4 v[18:19], v[148:151], off nt
	global_store_dwordx4 v[16:17], v[152:155], off nt
.LBB0_742:
	s_or_b64 exec, exec, s[10:11]
	v_add_u32_e32 v0, 0xa00, v8
	v_ashrrev_i32_e32 v16, 5, v0
	v_add_co_u32_e32 v0, vcc, 0xa000, v12
	v_mul_lo_u32 v17, v16, s72
	s_nop 0
	v_addc_co_u32_e32 v1, vcc, 0, v13, vcc
	v_add_co_u32_e32 v4, vcc, 0xa000, v10
	s_nop 0
	v_addc_co_u32_e32 v5, vcc, 0, v11, vcc
	v_add_u32_e32 v18, v14, v17
	v_add_u32_e32 v17, v15, v17
	v_cmp_lt_i32_e32 vcc, 0, v16
	s_waitcnt vmcnt(15)
	ds_write_b128 v18, v[156:159]
	s_waitcnt vmcnt(14)
	ds_write_b128 v17, v[160:163]
	s_and_saveexec_b64 s[10:11], vcc
	s_cbranch_execz .LBB0_744
	v_mov_b64_e32 v[16:17], 0x9e00
	v_lshl_add_u64 v[16:17], v[8:9], 4, v[16:17]
	v_lshl_add_u64 v[18:19], s[24:25], 0, v[16:17]
	v_lshl_add_u64 v[16:17], s[28:29], 0, v[16:17]
	global_store_dwordx4 v[18:19], v[156:159], off nt
	global_store_dwordx4 v[16:17], v[160:163], off nt
.LBB0_744:
	s_or_b64 exec, exec, s[10:11]
	v_add_u32_e32 v0, 0xc00, v8
	v_ashrrev_i32_e32 v16, 5, v0
	v_add_co_u32_e32 v0, vcc, 0xc000, v12
	v_mul_lo_u32 v17, v16, s72
	s_nop 0
	v_addc_co_u32_e32 v1, vcc, 0, v13, vcc
	v_add_co_u32_e32 v4, vcc, 0xc000, v10
	s_nop 0
	v_addc_co_u32_e32 v5, vcc, 0, v11, vcc
	v_add_u32_e32 v18, v14, v17
	v_add_u32_e32 v17, v15, v17
	v_cmp_lt_i32_e32 vcc, 0, v16
	s_waitcnt vmcnt(15)
	ds_write_b128 v18, v[184:187]
	s_waitcnt vmcnt(14)
	ds_write_b128 v17, v[188:191]
	s_and_saveexec_b64 s[10:11], vcc
	s_cbranch_execz .LBB0_746
	v_mov_b64_e32 v[16:17], 0xbe00
	v_lshl_add_u64 v[16:17], v[8:9], 4, v[16:17]
	v_lshl_add_u64 v[18:19], s[24:25], 0, v[16:17]
	v_lshl_add_u64 v[16:17], s[28:29], 0, v[16:17]
	global_store_dwordx4 v[18:19], v[184:187], off nt
	global_store_dwordx4 v[16:17], v[188:191], off nt
.LBB0_746:
	s_or_b64 exec, exec, s[10:11]
	v_add_co_u32_e32 v0, vcc, 0xe000, v12
	s_nop 1
	v_addc_co_u32_e32 v1, vcc, 0, v13, vcc
	v_add_co_u32_e32 v4, vcc, 0xe000, v10
	s_nop 0
	v_addc_co_u32_e32 v5, vcc, 0, v11, vcc
	v_add_u32_e32 v10, 0xe00, v8
	v_ashrrev_i32_e32 v10, 5, v10
	v_mul_lo_u32 v11, v10, s72
	v_add_u32_e32 v12, v14, v11
	v_cmp_lt_i32_e32 vcc, 0, v10
	v_add_u32_e32 v11, v15, v11
	s_waitcnt vmcnt(15)
	ds_write_b128 v12, v[192:195]
	s_waitcnt vmcnt(14)
	ds_write_b128 v11, v[196:199]
	s_and_saveexec_b64 s[10:11], vcc
	s_cbranch_execz .LBB0_748
	v_mov_b64_e32 v[10:11], 0xde00
	v_lshl_add_u64 v[10:11], v[8:9], 4, v[10:11]
	v_lshl_add_u64 v[12:13], s[24:25], 0, v[10:11]
	v_lshl_add_u64 v[10:11], s[28:29], 0, v[10:11]
	global_store_dwordx4 v[12:13], v[192:195], off nt
	global_store_dwordx4 v[10:11], v[196:199], off nt

.LBB0_1263:
	s_add_u32 s10, s46, 0xfffc0080
	s_addc_u32 s11, s47, -1
	s_add_i32 s69, 0, 0x10000
	v_add_u32_e32 v124, s69, v203
	ds_read_b128 v[112:115], v124
	ds_read_b128 v[116:119], v124 offset:1024
	ds_read_b128 v[120:123], v124 offset:2048
	ds_read_b128 v[124:127], v124 offset:3072
	s_cmp_eq_u32 s39, 12
	s_cselect_b32 s13, s16, s11
	s_cselect_b32 s12, s17, s10
	s_cselect_b32 s11, s20, s31
	s_cselect_b32 s10, s21, s27
	v_lshl_add_u64 v[208:209], s[46:47], 0, v[188:189]
	s_add_i32 m0, s54, 0xc000
	ds_read_b128 v[128:131], v206
	ds_read_b128 v[132:135], v206 offset:1024
	ds_read_b128 v[136:139], v206 offset:2048
	ds_read_b128 v[140:143], v206 offset:3072
	ds_read_b128 v[156:159], v206 offset:4096
	ds_read_b128 v[164:167], v206 offset:5120
	ds_read_b128 v[192:195], v206 offset:6144
	ds_read_b128 v[196:199], v206 offset:7168
	global_load_lds_dwordx4 v[208:209], off
	v_lshl_add_u64 v[208:209], s[46:47], 0, v[190:191]
	s_add_i32 m0, s54, 0xe000
	s_nop 0
	global_load_lds_dwordx4 v[208:209], off
	s_waitcnt lgkmcnt(8)
	s_barrier
	s_waitcnt lgkmcnt(0)
	s_setprio 1
	s_waitcnt lgkmcnt(0)
	v_mfma_f32_16x16x32_bf16 v[160:163], v[112:115], v[128:131], v[160:163]
	v_mfma_f32_16x16x32_bf16 v[152:155], v[120:123], v[128:131], v[152:155]
	v_mfma_f32_16x16x32_bf16 v[148:151], v[112:115], v[136:139], v[148:151]
	v_mfma_f32_16x16x32_bf16 v[144:147], v[120:123], v[136:139], v[144:147]
	v_mfma_f32_16x16x32_bf16 v[108:111], v[112:115], v[156:159], v[108:111]
	v_mfma_f32_16x16x32_bf16 v[104:107], v[120:123], v[156:159], v[104:107]
	v_mfma_f32_16x16x32_bf16 v[100:103], v[112:115], v[192:195], v[100:103]
	v_mfma_f32_16x16x32_bf16 v[96:99], v[120:123], v[192:195], v[96:99]
	v_mfma_f32_16x16x32_bf16 v[160:163], v[116:119], v[132:135], v[160:163]
	v_mfma_f32_16x16x32_bf16 v[152:155], v[124:127], v[132:135], v[152:155]
	v_mfma_f32_16x16x32_bf16 v[148:151], v[116:119], v[140:143], v[148:151]
	v_mfma_f32_16x16x32_bf16 v[144:147], v[124:127], v[140:143], v[144:147]
	v_mfma_f32_16x16x32_bf16 v[108:111], v[116:119], v[164:167], v[108:111]
	v_mfma_f32_16x16x32_bf16 v[104:107], v[124:127], v[164:167], v[104:107]
	v_mfma_f32_16x16x32_bf16 v[100:103], v[116:119], v[196:199], v[100:103]
	v_mfma_f32_16x16x32_bf16 v[96:99], v[124:127], v[196:199], v[96:99]
	s_setprio 0
	s_barrier
	s_add_i32 s78, 0, 0x14000
	s_add_i32 s69, s69, s45
	v_add_u32_e32 v168, s78, v203
	v_lshl_add_u64 v[224:225], s[10:11], 0, v[174:175]
	s_mov_b32 m0, s69
	ds_read_b128 v[208:211], v168
	ds_read_b128 v[212:215], v168 offset:1024
	ds_read_b128 v[216:219], v168 offset:2048
	ds_read_b128 v[220:223], v168 offset:3072
	global_load_lds_dwordx4 v[224:225], off
	v_lshl_add_u64 v[226:227], s[10:11], 0, v[182:183]
	s_add_i32 m0, s69, 0x2000
	s_nop 0
	global_load_lds_dwordx4 v[226:227], off
	s_barrier
	s_waitcnt lgkmcnt(0)
	s_setprio 1
	s_waitcnt lgkmcnt(0)
	v_mfma_f32_16x16x32_bf16 v[92:95], v[208:211], v[128:131], v[92:95]
	v_mfma_f32_16x16x32_bf16 v[88:91], v[216:219], v[128:131], v[88:91]
	v_mfma_f32_16x16x32_bf16 v[84:87], v[208:211], v[136:139], v[84:87]
	v_mfma_f32_16x16x32_bf16 v[80:83], v[216:219], v[136:139], v[80:83]
	v_mfma_f32_16x16x32_bf16 v[76:79], v[208:211], v[156:159], v[76:79]
	v_mfma_f32_16x16x32_bf16 v[72:75], v[216:219], v[156:159], v[72:75]
	v_mfma_f32_16x16x32_bf16 v[68:71], v[208:211], v[192:195], v[68:71]
	v_mfma_f32_16x16x32_bf16 v[64:67], v[216:219], v[192:195], v[64:67]
	v_mfma_f32_16x16x32_bf16 v[92:95], v[212:215], v[132:135], v[92:95]
	v_mfma_f32_16x16x32_bf16 v[88:91], v[220:223], v[132:135], v[88:91]
	v_mfma_f32_16x16x32_bf16 v[84:87], v[212:215], v[140:143], v[84:87]
	v_mfma_f32_16x16x32_bf16 v[80:83], v[220:223], v[140:143], v[80:83]
	v_mfma_f32_16x16x32_bf16 v[76:79], v[212:215], v[164:167], v[76:79]
	v_mfma_f32_16x16x32_bf16 v[72:75], v[220:223], v[164:167], v[72:75]
	v_mfma_f32_16x16x32_bf16 v[68:71], v[212:215], v[196:199], v[68:71]
	v_mfma_f32_16x16x32_bf16 v[64:67], v[220:223], v[196:199], v[64:67]
	s_setprio 0
	s_mov_b32 m0, s54
	v_lshl_add_u64 v[228:229], s[12:13], 0, v[186:187]
	s_barrier
	ds_read_b128 v[128:131], v206 offset:16384
	ds_read_b128 v[132:135], v206 offset:17408
	ds_read_b128 v[136:139], v206 offset:18432
	ds_read_b128 v[140:143], v206 offset:19456
	ds_read_b128 v[156:159], v206 offset:20480
	ds_read_b128 v[164:167], v206 offset:21504
	ds_read_b128 v[192:195], v206 offset:22528
	ds_read_b128 v[196:199], v206 offset:23552
	global_load_lds_dwordx4 v[228:229], off
	v_lshl_add_u64 v[230:231], s[12:13], 0, v[184:185]
	s_mov_b32 m0, s55
	s_nop 0
	global_load_lds_dwordx4 v[230:231], off
	s_barrier
	s_waitcnt lgkmcnt(0)
	s_setprio 1
	s_waitcnt lgkmcnt(0)
	v_mfma_f32_16x16x32_bf16 v[60:63], v[112:115], v[128:131], v[60:63]
	v_mfma_f32_16x16x32_bf16 v[56:59], v[120:123], v[128:131], v[56:59]
	v_mfma_f32_16x16x32_bf16 v[52:55], v[112:115], v[136:139], v[52:55]
	v_mfma_f32_16x16x32_bf16 v[48:51], v[120:123], v[136:139], v[48:51]
	v_mfma_f32_16x16x32_bf16 v[44:47], v[112:115], v[156:159], v[44:47]
	v_mfma_f32_16x16x32_bf16 v[40:43], v[120:123], v[156:159], v[40:43]
	v_mfma_f32_16x16x32_bf16 v[36:39], v[112:115], v[192:195], v[36:39]
	v_mfma_f32_16x16x32_bf16 v[32:35], v[120:123], v[192:195], v[32:35]
	v_mfma_f32_16x16x32_bf16 v[60:63], v[116:119], v[132:135], v[60:63]
	v_mfma_f32_16x16x32_bf16 v[56:59], v[124:127], v[132:135], v[56:59]
	v_mfma_f32_16x16x32_bf16 v[52:55], v[116:119], v[140:143], v[52:55]
	v_mfma_f32_16x16x32_bf16 v[48:51], v[124:127], v[140:143], v[48:51]
	v_mfma_f32_16x16x32_bf16 v[44:47], v[116:119], v[164:167], v[44:47]
	v_mfma_f32_16x16x32_bf16 v[40:43], v[124:127], v[164:167], v[40:43]
	v_mfma_f32_16x16x32_bf16 v[36:39], v[116:119], v[196:199], v[36:39]
	v_mfma_f32_16x16x32_bf16 v[32:35], v[124:127], v[196:199], v[32:35]
	s_setprio 0
	s_barrier
	s_add_u32 s76, s10, 0x40000
	s_addc_u32 s77, s11, 0
	s_add_i32 s69, s78, s45
	v_lshl_add_u64 v[112:113], s[76:77], 0, v[174:175]
	s_mov_b32 m0, s69
	s_nop 0
	global_load_lds_dwordx4 v[112:113], off
	v_lshl_add_u64 v[112:113], s[76:77], 0, v[182:183]
	s_add_i32 m0, s69, 0x2000
	s_nop 0
	global_load_lds_dwordx4 v[112:113], off
	s_waitcnt vmcnt(6)
	s_barrier
	s_setprio 1
	v_mfma_f32_16x16x32_bf16 v[28:31], v[208:211], v[128:131], v[28:31]
	v_mfma_f32_16x16x32_bf16 v[24:27], v[216:219], v[128:131], v[24:27]
	v_mfma_f32_16x16x32_bf16 v[20:23], v[208:211], v[136:139], v[20:23]
	v_mfma_f32_16x16x32_bf16 v[16:19], v[216:219], v[136:139], v[16:19]
	v_mfma_f32_16x16x32_bf16 v[12:15], v[208:211], v[156:159], v[12:15]
	v_mfma_f32_16x16x32_bf16 v[8:11], v[216:219], v[156:159], v[8:11]
	v_mfma_f32_16x16x32_bf16 v[4:7], v[208:211], v[192:195], v[4:7]
	v_mfma_f32_16x16x32_bf16 v[0:3], v[216:219], v[192:195], v[0:3]
	v_mfma_f32_16x16x32_bf16 v[28:31], v[212:215], v[132:135], v[28:31]
	v_mfma_f32_16x16x32_bf16 v[24:27], v[220:223], v[132:135], v[24:27]
	v_mfma_f32_16x16x32_bf16 v[20:23], v[212:215], v[140:143], v[20:23]
	v_mfma_f32_16x16x32_bf16 v[16:19], v[220:223], v[140:143], v[16:19]
	v_mfma_f32_16x16x32_bf16 v[12:15], v[212:215], v[164:167], v[12:15]
	v_mfma_f32_16x16x32_bf16 v[8:11], v[220:223], v[164:167], v[8:11]
	v_mfma_f32_16x16x32_bf16 v[4:7], v[212:215], v[196:199], v[4:7]
	v_mfma_f32_16x16x32_bf16 v[0:3], v[220:223], v[196:199], v[0:3]
	s_setprio 0
	s_add_i32 s69, 0, 0x18000
	v_add_u32_e32 v124, s69, v203
	s_barrier
	ds_read_b128 v[112:115], v124
	ds_read_b128 v[116:119], v124 offset:1024
	ds_read_b128 v[120:123], v124 offset:2048
	ds_read_b128 v[124:127], v124 offset:3072
	s_add_u32 s12, s12, 0x40000
	s_addc_u32 s13, s13, 0
	s_mov_b32 m0, s58
	v_lshl_add_u64 v[208:209], s[12:13], 0, v[186:187]
	ds_read_b128 v[128:131], v206 offset:32768
	ds_read_b128 v[132:135], v206 offset:33792
	ds_read_b128 v[136:139], v206 offset:34816
	ds_read_b128 v[140:143], v206 offset:35840
	ds_read_b128 v[156:159], v206 offset:36864
	ds_read_b128 v[164:167], v206 offset:37888
	ds_read_b128 v[192:195], v206 offset:38912
	ds_read_b128 v[196:199], v206 offset:39936
	global_load_lds_dwordx4 v[208:209], off
	v_lshl_add_u64 v[208:209], s[12:13], 0, v[184:185]
	s_mov_b32 m0, s59
	s_nop 0
	global_load_lds_dwordx4 v[208:209], off
	s_waitcnt lgkmcnt(8)
	s_barrier
	s_waitcnt lgkmcnt(0)
	s_setprio 1
	s_waitcnt lgkmcnt(0)
	v_mfma_f32_16x16x32_bf16 v[160:163], v[112:115], v[128:131], v[160:163]
	v_mfma_f32_16x16x32_bf16 v[152:155], v[120:123], v[128:131], v[152:155]
	v_mfma_f32_16x16x32_bf16 v[148:151], v[112:115], v[136:139], v[148:151]
	v_mfma_f32_16x16x32_bf16 v[144:147], v[120:123], v[136:139], v[144:147]
	v_mfma_f32_16x16x32_bf16 v[108:111], v[112:115], v[156:159], v[108:111]
	v_mfma_f32_16x16x32_bf16 v[104:107], v[120:123], v[156:159], v[104:107]
	v_mfma_f32_16x16x32_bf16 v[100:103], v[112:115], v[192:195], v[100:103]
	v_mfma_f32_16x16x32_bf16 v[96:99], v[120:123], v[192:195], v[96:99]
	v_mfma_f32_16x16x32_bf16 v[160:163], v[116:119], v[132:135], v[160:163]
	v_mfma_f32_16x16x32_bf16 v[152:155], v[124:127], v[132:135], v[152:155]
	v_mfma_f32_16x16x32_bf16 v[148:151], v[116:119], v[140:143], v[148:151]
	v_mfma_f32_16x16x32_bf16 v[144:147], v[124:127], v[140:143], v[144:147]
	v_mfma_f32_16x16x32_bf16 v[108:111], v[116:119], v[164:167], v[108:111]
	v_mfma_f32_16x16x32_bf16 v[104:107], v[124:127], v[164:167], v[104:107]
	v_mfma_f32_16x16x32_bf16 v[100:103], v[116:119], v[196:199], v[100:103]
	v_mfma_f32_16x16x32_bf16 v[96:99], v[124:127], v[196:199], v[96:99]
	s_setprio 0
	s_barrier
	s_add_i32 s12, 0, 0x1c000
	s_add_i32 s13, s69, s45
	v_add_u32_e32 v168, s12, v203
	v_lshl_add_u64 v[224:225], v[224:225], 0, s[8:9]
	s_mov_b32 m0, s13
	ds_read_b128 v[208:211], v168
	ds_read_b128 v[212:215], v168 offset:1024
	ds_read_b128 v[216:219], v168 offset:2048
	ds_read_b128 v[220:223], v168 offset:3072
	global_load_lds_dwordx4 v[224:225], off
	v_lshl_add_u64 v[224:225], v[226:227], 0, s[8:9]
	s_add_i32 m0, s13, 0x2000
	s_nop 0
	global_load_lds_dwordx4 v[224:225], off
	s_barrier
	s_waitcnt lgkmcnt(0)
	s_setprio 1
	s_waitcnt lgkmcnt(0)
	v_mfma_f32_16x16x32_bf16 v[92:95], v[208:211], v[128:131], v[92:95]
	v_mfma_f32_16x16x32_bf16 v[88:91], v[216:219], v[128:131], v[88:91]
	v_mfma_f32_16x16x32_bf16 v[84:87], v[208:211], v[136:139], v[84:87]
	v_mfma_f32_16x16x32_bf16 v[80:83], v[216:219], v[136:139], v[80:83]
	v_mfma_f32_16x16x32_bf16 v[76:79], v[208:211], v[156:159], v[76:79]
	v_mfma_f32_16x16x32_bf16 v[72:75], v[216:219], v[156:159], v[72:75]
	v_mfma_f32_16x16x32_bf16 v[68:71], v[208:211], v[192:195], v[68:71]
	v_mfma_f32_16x16x32_bf16 v[64:67], v[216:219], v[192:195], v[64:67]
	v_mfma_f32_16x16x32_bf16 v[92:95], v[212:215], v[132:135], v[92:95]
	v_mfma_f32_16x16x32_bf16 v[88:91], v[220:223], v[132:135], v[88:91]
	v_mfma_f32_16x16x32_bf16 v[84:87], v[212:215], v[140:143], v[84:87]
	v_mfma_f32_16x16x32_bf16 v[80:83], v[220:223], v[140:143], v[80:83]
	v_mfma_f32_16x16x32_bf16 v[76:79], v[212:215], v[164:167], v[76:79]
	v_mfma_f32_16x16x32_bf16 v[72:75], v[220:223], v[164:167], v[72:75]
	v_mfma_f32_16x16x32_bf16 v[68:71], v[212:215], v[196:199], v[68:71]
	v_mfma_f32_16x16x32_bf16 v[64:67], v[220:223], v[196:199], v[64:67]
	s_setprio 0
	s_mov_b32 m0, s62
	v_lshl_add_u64 v[224:225], v[228:229], 0, s[8:9]
	s_barrier
	ds_read_b128 v[128:131], v206 offset:49152
	ds_read_b128 v[132:135], v206 offset:50176
	ds_read_b128 v[136:139], v206 offset:51200
	ds_read_b128 v[140:143], v206 offset:52224
	ds_read_b128 v[156:159], v206 offset:53248
	ds_read_b128 v[164:167], v206 offset:54272
	ds_read_b128 v[192:195], v206 offset:55296
	ds_read_b128 v[196:199], v206 offset:56320
	global_load_lds_dwordx4 v[224:225], off
	v_lshl_add_u64 v[224:225], v[230:231], 0, s[8:9]
	s_mov_b32 m0, s63
	s_nop 0
	global_load_lds_dwordx4 v[224:225], off
	s_barrier
	s_waitcnt lgkmcnt(0)
	s_setprio 1
	s_waitcnt lgkmcnt(0)
	v_mfma_f32_16x16x32_bf16 v[60:63], v[112:115], v[128:131], v[60:63]
	v_mfma_f32_16x16x32_bf16 v[56:59], v[120:123], v[128:131], v[56:59]
	v_mfma_f32_16x16x32_bf16 v[52:55], v[112:115], v[136:139], v[52:55]
	v_mfma_f32_16x16x32_bf16 v[48:51], v[120:123], v[136:139], v[48:51]
	v_mfma_f32_16x16x32_bf16 v[44:47], v[112:115], v[156:159], v[44:47]
	v_mfma_f32_16x16x32_bf16 v[40:43], v[120:123], v[156:159], v[40:43]
	v_mfma_f32_16x16x32_bf16 v[36:39], v[112:115], v[192:195], v[36:39]
	v_mfma_f32_16x16x32_bf16 v[32:35], v[120:123], v[192:195], v[32:35]
	v_mfma_f32_16x16x32_bf16 v[60:63], v[116:119], v[132:135], v[60:63]
	v_mfma_f32_16x16x32_bf16 v[56:59], v[124:127], v[132:135], v[56:59]
	v_mfma_f32_16x16x32_bf16 v[52:55], v[116:119], v[140:143], v[52:55]
	v_mfma_f32_16x16x32_bf16 v[48:51], v[124:127], v[140:143], v[48:51]
	v_mfma_f32_16x16x32_bf16 v[44:47], v[116:119], v[164:167], v[44:47]
	v_mfma_f32_16x16x32_bf16 v[40:43], v[124:127], v[164:167], v[40:43]
	v_mfma_f32_16x16x32_bf16 v[36:39], v[116:119], v[196:199], v[36:39]
	v_mfma_f32_16x16x32_bf16 v[32:35], v[124:127], v[196:199], v[32:35]
	s_setprio 0
	s_barrier
	s_add_u32 s10, s10, 0x40080
	s_addc_u32 s11, s11, 0
	s_add_i32 s12, s12, s45
	v_lshl_add_u64 v[112:113], s[10:11], 0, v[174:175]
	s_mov_b32 m0, s12
	s_nop 0
	global_load_lds_dwordx4 v[112:113], off
	v_lshl_add_u64 v[112:113], s[10:11], 0, v[182:183]
	s_add_i32 m0, s12, 0x2000
	s_nop 0
	global_load_lds_dwordx4 v[112:113], off
	s_waitcnt vmcnt(6)
	s_barrier
	s_setprio 1
	v_mfma_f32_16x16x32_bf16 v[28:31], v[208:211], v[128:131], v[28:31]
	v_mfma_f32_16x16x32_bf16 v[24:27], v[216:219], v[128:131], v[24:27]
	v_mfma_f32_16x16x32_bf16 v[20:23], v[208:211], v[136:139], v[20:23]
	v_mfma_f32_16x16x32_bf16 v[16:19], v[216:219], v[136:139], v[16:19]
	v_mfma_f32_16x16x32_bf16 v[12:15], v[208:211], v[156:159], v[12:15]
	v_mfma_f32_16x16x32_bf16 v[8:11], v[216:219], v[156:159], v[8:11]
	v_mfma_f32_16x16x32_bf16 v[4:7], v[208:211], v[192:195], v[4:7]
	v_mfma_f32_16x16x32_bf16 v[0:3], v[216:219], v[192:195], v[0:3]
	v_mfma_f32_16x16x32_bf16 v[28:31], v[212:215], v[132:135], v[28:31]
	v_mfma_f32_16x16x32_bf16 v[24:27], v[220:223], v[132:135], v[24:27]
	v_mfma_f32_16x16x32_bf16 v[20:23], v[212:215], v[140:143], v[20:23]
	v_mfma_f32_16x16x32_bf16 v[16:19], v[220:223], v[140:143], v[16:19]
	v_mfma_f32_16x16x32_bf16 v[12:15], v[212:215], v[164:167], v[12:15]
	v_mfma_f32_16x16x32_bf16 v[8:11], v[220:223], v[164:167], v[8:11]
	v_mfma_f32_16x16x32_bf16 v[4:7], v[212:215], v[196:199], v[4:7]
	v_mfma_f32_16x16x32_bf16 v[0:3], v[220:223], v[196:199], v[0:3]
	s_setprio 0
	s_add_i32 s39, s39, 2
	s_add_u32 s46, s46, 0x100
	s_addc_u32 s47, s47, 0
	s_add_u32 s27, s27, 0x100
	s_addc_u32 s31, s31, 0
	s_cmp_gt_u32 s39, 13
	s_barrier
	s_cbranch_scc0 .LBB0_1263
	v_lshrrev_b32_e32 v226, 2, v237
	v_and_b32_e32 v227, 15, v237
	v_sub_u32_e32 v226, v226, v227
	v_lshlrev_b32_e32 v226, 13, v226
	v_and_b32_e32 v227, 3, v237
	v_lshrrev_b32_e32 v225, 4, v237
	v_sub_u32_e32 v227, v227, v225
	v_lshl_add_u32 v226, v227, 4, v226
	v_ashrrev_i32_e32 v227, 31, v226
	v_and_b32_e32 v225, 3, v237
	v_lshlrev_b32_e32 v225, 6, v225
	v_and_b32_e32 v224, 60, v237
	v_or_b32_e32 v224, v224, v225
	s_mov_b64 s[10:11], s[0:1]
	s_load_dwordx2 s[10:11], s[10:11], 0xd0
	s_mov_b32 s12, s44
	s_lshl_b32 s12, s12, 12
	s_ashr_i32 s13, s12, 31
	s_lshl_b64 s[12:13], s[12:13], 2
	s_waitcnt lgkmcnt(0)
	s_add_u32 s12, s10, s12
	v_lshl_or_b32 v192, s26, 8, v205
	s_addc_u32 s13, s11, s13
	v_ashrrev_i32_e32 v193, 31, v192
	v_lshl_add_u64 v[112:113], v[192:193], 2, s[12:13]
	s_mov_b64 s[12:13], 0xef8e000
	v_lshl_add_u64 v[116:117], v[112:113], 0, s[12:13]
	s_mov_b32 s12, 0xef8e000
	v_add_co_u32_e32 v114, vcc, s12, v112
	s_mov_b64 s[12:13], 0xef96000
	s_nop 0
	v_addc_co_u32_e32 v115, vcc, 0, v113, vcc
	v_lshl_add_u64 v[124:125], v[112:113], 0, s[12:13]
	s_mov_b32 s12, 0xef96000
	global_load_dwordx4 v[128:131], v[114:115], off
	global_load_dwordx4 v[132:135], v[116:117], off offset:16
	v_add_co_u32_e32 v112, vcc, s12, v112
	v_lshl_add_u32 v207, s25, 11, v204
	s_nop 0
	v_addc_co_u32_e32 v113, vcc, 0, v113, vcc
	global_load_dwordx4 v[136:139], v[112:113], off
	global_load_dwordx4 v[140:143], v[124:125], off offset:16
	s_nop 0
	global_load_dwordx4 v[112:115], v[116:117], off offset:528
	global_load_dwordx4 v[120:123], v[116:117], off offset:512
	s_nop 0
	global_load_dwordx4 v[116:119], v[124:125], off offset:528
	s_nop 0
	global_load_dwordx4 v[124:127], v[124:125], off offset:512
	ds_read2_b64 v[164:167], v207 offset1:16
	ds_read2_b64 v[156:159], v207 offset0:32 offset1:48
	s_add_u32 s46, s10, 0x6a80000
	v_lshl_add_u32 v198, s24, 8, v178
	s_addc_u32 s47, s11, 0
	v_ashrrev_i32_e32 v199, 31, v198
	v_or_b32_e32 v196, 0x80, v192
	v_lshl_add_u64 v[192:193], v[192:193], 1, s[46:47]
	v_ashrrev_i32_e32 v197, 31, v196
	s_mov_b64 s[10:11], 0x100000
	s_and_b64 vcc, exec, s[28:29]
	s_mov_b32 s26, s30
	s_mov_b32 s24, s38
	s_mov_b64 s[12:13], s[40:41]
	s_mov_b32 s25, s68
	s_waitcnt vmcnt(0)
	v_xor_b32_e32 v195, 0x80000000, v131
	v_xor_b32_e32 v194, 0x80000000, v130
	s_waitcnt lgkmcnt(1)
	v_pk_fma_f32 v[130:131], v[194:195], v[164:165], v[162:163] op_sel_hi:[1,0,1]
	v_pk_fma_f32 v[160:161], v[128:129], v[164:165], v[160:161] op_sel_hi:[1,0,1] neg_lo:[1,0,0] neg_hi:[1,0,0]
	v_pk_fma_f32 v[152:153], v[132:133], v[164:165], v[152:153] op_sel_hi:[1,0,1] neg_lo:[1,0,0] neg_hi:[1,0,0]
	v_pk_fma_f32 v[148:149], v[128:129], v[166:167], v[148:149] op_sel_hi:[1,0,1] neg_lo:[1,0,0] neg_hi:[1,0,0]
	v_pk_fma_f32 v[130:131], v[164:165], v[130:131], v[138:139] op_sel:[1,0,0]
	v_pk_fma_f32 v[160:161], v[164:165], v[160:161], v[136:137] op_sel:[1,0,0]
	v_max_f32_e32 v130, 0, v130
	v_max_f32_e32 v131, 0, v131
	v_pk_mul_f32 v[162:163], v[130:131], v[130:131]
	v_xor_b32_e32 v131, 0x80000000, v135
	v_xor_b32_e32 v130, 0x80000000, v134
	v_pk_fma_f32 v[134:135], v[130:131], v[164:165], v[154:155] op_sel_hi:[1,0,1]
	v_pk_fma_f32 v[152:153], v[164:165], v[152:153], v[140:141] op_sel:[1,0,0]
	v_pk_fma_f32 v[134:135], v[164:165], v[134:135], v[142:143] op_sel:[1,0,0]
	v_max_f32_e32 v160, 0, v160
	v_max_f32_e32 v134, 0, v134
	v_max_f32_e32 v135, 0, v135
	v_max_f32_e32 v161, 0, v161
	v_max_f32_e32 v152, 0, v152
	v_max_f32_e32 v153, 0, v153
	v_pk_mul_f32 v[208:209], v[134:135], v[134:135]
	v_lshlrev_b64 v[134:135], 13, v[198:199]
	v_pk_fma_f32 v[146:147], v[130:131], v[166:167], v[146:147] op_sel_hi:[1,0,1]
	v_pk_fma_f32 v[144:145], v[132:133], v[166:167], v[144:145] op_sel_hi:[1,0,1] neg_lo:[1,0,0] neg_hi:[1,0,0]
	v_pk_mul_f32 v[160:161], v[160:161], v[160:161]
	v_pk_mul_f32 v[154:155], v[152:153], v[152:153]
	v_lshl_add_u64 v[210:211], v[192:193], 0, v[134:135]
	v_cvt_pk_bf16_f32 v152, v160, v161
	v_cvt_pk_bf16_f32 v153, v162, v163
	v_pk_fma_f32 v[150:151], v[194:195], v[166:167], v[150:151] op_sel_hi:[1,0,1]
	v_pk_fma_f32 v[148:149], v[166:167], v[148:149], v[136:137] op_sel:[1,0,0]
	v_pk_fma_f32 v[146:147], v[166:167], v[146:147], v[142:143] op_sel:[1,0,0]
	v_pk_fma_f32 v[144:145], v[166:167], v[144:145], v[140:141] op_sel:[1,0,0]
	v_cvt_pk_bf16_f32 v154, v154, v155
	v_cvt_pk_bf16_f32 v155, v208, v209
	ds_bpermute_b32 v212, v224, v152
	ds_bpermute_b32 v213, v224, v153
	ds_bpermute_b32 v214, v224, v154
	ds_bpermute_b32 v215, v224, v155
	v_lshl_add_u64 v[220:221], v[210:211], 0, v[226:227]
	v_pk_fma_f32 v[150:151], v[166:167], v[150:151], v[138:139] op_sel:[1,0,0]
	v_max_f32_e32 v144, 0, v144
	v_max_f32_e32 v152, 0, v148
	v_max_f32_e32 v153, 0, v149
	v_max_f32_e32 v145, 0, v145
	v_max_f32_e32 v146, 0, v146
	v_max_f32_e32 v147, 0, v147
	v_or_b32_e32 v154, 16, v198
	v_max_f32_e32 v148, 0, v150
	v_max_f32_e32 v149, 0, v151
	v_pk_mul_f32 v[150:151], v[152:153], v[152:153]
	v_pk_mul_f32 v[146:147], v[146:147], v[146:147]
	v_pk_mul_f32 v[152:153], v[144:145], v[144:145]
	v_pk_mul_f32 v[148:149], v[148:149], v[148:149]
	v_ashrrev_i32_e32 v155, 31, v154
	v_cvt_pk_bf16_f32 v150, v150, v151
	v_cvt_pk_bf16_f32 v151, v148, v149
	v_cvt_pk_bf16_f32 v152, v152, v153
	v_cvt_pk_bf16_f32 v153, v146, v147
	v_or_b32_e32 v146, 32, v198
	s_waitcnt lgkmcnt(0)
	v_pk_fma_f32 v[108:109], v[128:129], v[156:157], v[108:109] op_sel_hi:[1,0,1] neg_lo:[1,0,0] neg_hi:[1,0,0]
	v_pk_fma_f32 v[106:107], v[130:131], v[156:157], v[106:107] op_sel_hi:[1,0,1]
	v_pk_fma_f32 v[104:105], v[132:133], v[156:157], v[104:105] op_sel_hi:[1,0,1] neg_lo:[1,0,0] neg_hi:[1,0,0]
	v_lshlrev_b64 v[144:145], 13, v[154:155]
	v_pk_fma_f32 v[110:111], v[194:195], v[156:157], v[110:111] op_sel_hi:[1,0,1]
	v_pk_fma_f32 v[108:109], v[156:157], v[108:109], v[136:137] op_sel:[1,0,0]
	v_pk_fma_f32 v[106:107], v[156:157], v[106:107], v[142:143] op_sel:[1,0,0]
	v_pk_fma_f32 v[104:105], v[156:157], v[104:105], v[140:141] op_sel:[1,0,0]
	v_ashrrev_i32_e32 v147, 31, v146
	v_lshl_add_u64 v[154:155], v[192:193], 0, v[144:145]
	v_pk_fma_f32 v[110:111], v[156:157], v[110:111], v[138:139] op_sel:[1,0,0]
	v_max_f32_e32 v108, 0, v108
	v_max_f32_e32 v109, 0, v109
	v_max_f32_e32 v104, 0, v104
	v_max_f32_e32 v105, 0, v105
	v_max_f32_e32 v106, 0, v106
	v_max_f32_e32 v107, 0, v107
	v_lshlrev_b64 v[146:147], 13, v[146:147]
	s_waitcnt lgkmcnt(0)
	global_store_dwordx4 v[220:221], v[212:215], off sc1
	ds_bpermute_b32 v216, v224, v150
	ds_bpermute_b32 v217, v224, v151
	ds_bpermute_b32 v218, v224, v152
	ds_bpermute_b32 v219, v224, v153
	v_lshl_add_u64 v[222:223], v[154:155], 0, v[226:227]
	v_max_f32_e32 v110, 0, v110
	v_max_f32_e32 v111, 0, v111
	v_pk_mul_f32 v[108:109], v[108:109], v[108:109]
	v_pk_mul_f32 v[148:149], v[106:107], v[106:107]
	v_pk_mul_f32 v[106:107], v[104:105], v[104:105]
	v_lshl_add_u64 v[150:151], v[192:193], 0, v[146:147]
	v_cvt_pk_bf16_f32 v104, v108, v109
	v_pk_fma_f32 v[98:99], v[130:131], v[158:159], v[98:99] op_sel_hi:[1,0,1]
	v_pk_fma_f32 v[96:97], v[132:133], v[158:159], v[96:97] op_sel_hi:[1,0,1] neg_lo:[1,0,0] neg_hi:[1,0,0]
	v_pk_mul_f32 v[110:111], v[110:111], v[110:111]
	v_pk_fma_f32 v[102:103], v[194:195], v[158:159], v[102:103] op_sel_hi:[1,0,1]
	v_cvt_pk_bf16_f32 v105, v110, v111
	v_cvt_pk_bf16_f32 v106, v106, v107
	v_cvt_pk_bf16_f32 v107, v148, v149
	s_waitcnt lgkmcnt(0)
	global_store_dwordx4 v[222:223], v[216:219], off sc1
	ds_bpermute_b32 v212, v224, v104
	ds_bpermute_b32 v213, v224, v105
	ds_bpermute_b32 v214, v224, v106
	ds_bpermute_b32 v215, v224, v107
	v_lshl_add_u64 v[220:221], v[150:151], 0, v[226:227]
	v_pk_fma_f32 v[100:101], v[128:129], v[158:159], v[100:101] op_sel_hi:[1,0,1] neg_lo:[1,0,0] neg_hi:[1,0,0]
	v_pk_fma_f32 v[98:99], v[158:159], v[98:99], v[142:143] op_sel:[1,0,0]
	v_or_b32_e32 v104, 48, v198
	v_pk_fma_f32 v[96:97], v[158:159], v[96:97], v[140:141] op_sel:[1,0,0]
	v_pk_fma_f32 v[102:103], v[158:159], v[102:103], v[138:139] op_sel:[1,0,0]
	v_pk_fma_f32 v[100:101], v[158:159], v[100:101], v[136:137] op_sel:[1,0,0]
	v_max_f32_e32 v96, 0, v96
	v_max_f32_e32 v97, 0, v97
	v_max_f32_e32 v98, 0, v98
	v_max_f32_e32 v99, 0, v99
	v_ashrrev_i32_e32 v105, 31, v104
	v_pk_fma_f32 v[92:93], v[120:121], v[164:165], v[92:93] op_sel_hi:[1,0,1] neg_lo:[1,0,0] neg_hi:[1,0,0]
	v_max_f32_e32 v100, 0, v100
	v_max_f32_e32 v101, 0, v101
	v_max_f32_e32 v102, 0, v102
	v_max_f32_e32 v103, 0, v103
	v_pk_mul_f32 v[106:107], v[98:99], v[98:99]
	v_pk_mul_f32 v[98:99], v[96:97], v[96:97]
	v_lshlrev_b64 v[104:105], 13, v[104:105]
	v_pk_fma_f32 v[92:93], v[164:165], v[92:93], v[124:125] op_sel:[1,0,0]
	v_pk_mul_f32 v[102:103], v[102:103], v[102:103]
	v_pk_mul_f32 v[100:101], v[100:101], v[100:101]
	v_lshl_add_u64 v[108:109], v[192:193], 0, v[104:105]
	v_cvt_pk_bf16_f32 v96, v100, v101
	v_cvt_pk_bf16_f32 v97, v102, v103
	v_cvt_pk_bf16_f32 v98, v98, v99
	v_cvt_pk_bf16_f32 v99, v106, v107
	v_max_f32_e32 v92, 0, v92
	v_max_f32_e32 v93, 0, v93
	s_waitcnt lgkmcnt(0)
	global_store_dwordx4 v[220:221], v[212:215], off sc1
	ds_bpermute_b32 v216, v224, v96
	ds_bpermute_b32 v217, v224, v97
	ds_bpermute_b32 v218, v224, v98
	ds_bpermute_b32 v219, v224, v99
	v_lshl_add_u64 v[222:223], v[108:109], 0, v[226:227]
	v_pk_fma_f32 v[88:89], v[112:113], v[164:165], v[88:89] op_sel_hi:[1,0,1] neg_lo:[1,0,0] neg_hi:[1,0,0]
	v_pk_fma_f32 v[80:81], v[112:113], v[166:167], v[80:81] op_sel_hi:[1,0,1] neg_lo:[1,0,0] neg_hi:[1,0,0]
	v_pk_mul_f32 v[98:99], v[92:93], v[92:93]
	v_xor_b32_e32 v93, 0x80000000, v115
	v_xor_b32_e32 v92, 0x80000000, v114
	v_xor_b32_e32 v97, 0x80000000, v123
	v_xor_b32_e32 v96, 0x80000000, v122
	v_pk_fma_f32 v[90:91], v[92:93], v[164:165], v[90:91] op_sel_hi:[1,0,1]
	v_pk_fma_f32 v[94:95], v[96:97], v[164:165], v[94:95] op_sel_hi:[1,0,1]
	v_pk_fma_f32 v[90:91], v[164:165], v[90:91], v[118:119] op_sel:[1,0,0]
	v_pk_fma_f32 v[88:89], v[164:165], v[88:89], v[116:117] op_sel:[1,0,0]
	v_pk_fma_f32 v[82:83], v[92:93], v[166:167], v[82:83] op_sel_hi:[1,0,1]
	v_pk_fma_f32 v[94:95], v[164:165], v[94:95], v[126:127] op_sel:[1,0,0]
	v_max_f32_e32 v88, 0, v88
	v_max_f32_e32 v89, 0, v89
	v_max_f32_e32 v90, 0, v90
	v_max_f32_e32 v91, 0, v91
	v_pk_fma_f32 v[86:87], v[96:97], v[166:167], v[86:87] op_sel_hi:[1,0,1]
	v_pk_fma_f32 v[84:85], v[120:121], v[166:167], v[84:85] op_sel_hi:[1,0,1] neg_lo:[1,0,0] neg_hi:[1,0,0]
	v_pk_fma_f32 v[82:83], v[166:167], v[82:83], v[118:119] op_sel:[1,0,0]
	v_pk_fma_f32 v[80:81], v[166:167], v[80:81], v[116:117] op_sel:[1,0,0]
	v_max_f32_e32 v94, 0, v94
	v_max_f32_e32 v95, 0, v95
	v_pk_mul_f32 v[90:91], v[90:91], v[90:91]
	v_pk_mul_f32 v[100:101], v[88:89], v[88:89]
	v_lshl_add_u64 v[102:103], s[46:47], 0, v[134:135]
	v_lshlrev_b64 v[88:89], 1, v[196:197]
	v_pk_fma_f32 v[86:87], v[166:167], v[86:87], v[126:127] op_sel:[1,0,0]
	v_pk_fma_f32 v[84:85], v[166:167], v[84:85], v[124:125] op_sel:[1,0,0]
	v_max_f32_e32 v80, 0, v80
	v_max_f32_e32 v81, 0, v81
	v_max_f32_e32 v82, 0, v82
	v_max_f32_e32 v83, 0, v83
	v_pk_fma_f32 v[74:75], v[92:93], v[156:157], v[74:75] op_sel_hi:[1,0,1]
	v_pk_fma_f32 v[72:73], v[112:113], v[156:157], v[72:73] op_sel_hi:[1,0,1] neg_lo:[1,0,0] neg_hi:[1,0,0]
	v_pk_mul_f32 v[94:95], v[94:95], v[94:95]
	v_lshl_add_u64 v[102:103], v[102:103], 0, v[88:89]
	v_cvt_pk_bf16_f32 v98, v98, v99
	v_cvt_pk_bf16_f32 v99, v94, v95
	v_cvt_pk_bf16_f32 v100, v100, v101
	v_cvt_pk_bf16_f32 v101, v90, v91
	v_max_f32_e32 v84, 0, v84
	v_max_f32_e32 v85, 0, v85
	v_max_f32_e32 v86, 0, v86
	v_max_f32_e32 v87, 0, v87
	v_pk_mul_f32 v[90:91], v[82:83], v[82:83]
	v_pk_mul_f32 v[82:83], v[80:81], v[80:81]
	v_lshl_add_u64 v[80:81], s[46:47], 0, v[144:145]
	v_pk_fma_f32 v[78:79], v[96:97], v[156:157], v[78:79] op_sel_hi:[1,0,1]
	v_pk_fma_f32 v[76:77], v[120:121], v[156:157], v[76:77] op_sel_hi:[1,0,1] neg_lo:[1,0,0] neg_hi:[1,0,0]
	v_pk_fma_f32 v[74:75], v[156:157], v[74:75], v[118:119] op_sel:[1,0,0]
	v_pk_fma_f32 v[72:73], v[156:157], v[72:73], v[116:117] op_sel:[1,0,0]
	s_waitcnt lgkmcnt(0)
	global_store_dwordx4 v[222:223], v[216:219], off sc1
	ds_bpermute_b32 v212, v224, v98
	ds_bpermute_b32 v213, v224, v99
	ds_bpermute_b32 v214, v224, v100
	ds_bpermute_b32 v215, v224, v101
	v_lshl_add_u64 v[220:221], v[102:103], 0, v[226:227]
	v_pk_mul_f32 v[86:87], v[86:87], v[86:87]
	v_pk_mul_f32 v[84:85], v[84:85], v[84:85]
	v_lshl_add_u64 v[94:95], v[80:81], 0, v[88:89]
	v_cvt_pk_bf16_f32 v80, v84, v85
	v_cvt_pk_bf16_f32 v81, v86, v87
	v_pk_fma_f32 v[78:79], v[156:157], v[78:79], v[126:127] op_sel:[1,0,0]
	v_pk_fma_f32 v[76:77], v[156:157], v[76:77], v[124:125] op_sel:[1,0,0]
	v_max_f32_e32 v72, 0, v72
	v_max_f32_e32 v73, 0, v73
	v_max_f32_e32 v74, 0, v74
	v_max_f32_e32 v75, 0, v75
	v_pk_fma_f32 v[66:67], v[92:93], v[158:159], v[66:67] op_sel_hi:[1,0,1]
	v_pk_fma_f32 v[64:65], v[112:113], v[158:159], v[64:65] op_sel_hi:[1,0,1] neg_lo:[1,0,0] neg_hi:[1,0,0]
	v_cvt_pk_bf16_f32 v82, v82, v83
	v_cvt_pk_bf16_f32 v83, v90, v91
	s_waitcnt lgkmcnt(0)
	global_store_dwordx4 v[220:221], v[212:215], off sc1
	ds_bpermute_b32 v216, v224, v80
	ds_bpermute_b32 v217, v224, v81
	ds_bpermute_b32 v218, v224, v82
	ds_bpermute_b32 v219, v224, v83
	v_lshl_add_u64 v[222:223], v[94:95], 0, v[226:227]
	v_max_f32_e32 v76, 0, v76
	v_max_f32_e32 v77, 0, v77
	v_max_f32_e32 v78, 0, v78
	v_max_f32_e32 v79, 0, v79
	v_pk_mul_f32 v[80:81], v[74:75], v[74:75]
	v_pk_mul_f32 v[74:75], v[72:73], v[72:73]
	v_lshl_add_u64 v[72:73], s[46:47], 0, v[146:147]
	v_pk_fma_f32 v[66:67], v[158:159], v[66:67], v[118:119] op_sel:[1,0,0]
	v_pk_fma_f32 v[64:65], v[158:159], v[64:65], v[116:117] op_sel:[1,0,0]
	v_pk_mul_f32 v[78:79], v[78:79], v[78:79]
	v_pk_mul_f32 v[76:77], v[76:77], v[76:77]
	v_lshl_add_u64 v[82:83], v[72:73], 0, v[88:89]
	v_cvt_pk_bf16_f32 v72, v76, v77
	v_cvt_pk_bf16_f32 v73, v78, v79
	v_pk_fma_f32 v[70:71], v[96:97], v[158:159], v[70:71] op_sel_hi:[1,0,1]
	v_pk_fma_f32 v[68:69], v[120:121], v[158:159], v[68:69] op_sel_hi:[1,0,1] neg_lo:[1,0,0] neg_hi:[1,0,0]
	v_max_f32_e32 v64, 0, v64
	v_max_f32_e32 v65, 0, v65
	v_max_f32_e32 v66, 0, v66
	v_max_f32_e32 v67, 0, v67
	v_cvt_pk_bf16_f32 v74, v74, v75
	v_cvt_pk_bf16_f32 v75, v80, v81
	s_waitcnt lgkmcnt(0)
	global_store_dwordx4 v[222:223], v[216:219], off sc1
	ds_bpermute_b32 v212, v224, v72
	ds_bpermute_b32 v213, v224, v73
	ds_bpermute_b32 v214, v224, v74
	ds_bpermute_b32 v215, v224, v75
	v_lshl_add_u64 v[220:221], v[82:83], 0, v[226:227]
	v_pk_fma_f32 v[70:71], v[158:159], v[70:71], v[126:127] op_sel:[1,0,0]
	v_pk_fma_f32 v[68:69], v[158:159], v[68:69], v[124:125] op_sel:[1,0,0]
	v_pk_mul_f32 v[72:73], v[66:67], v[66:67]
	v_pk_mul_f32 v[66:67], v[64:65], v[64:65]
	v_lshl_add_u64 v[64:65], s[46:47], 0, v[104:105]
	v_max_f32_e32 v68, 0, v68
	v_max_f32_e32 v69, 0, v69
	v_max_f32_e32 v70, 0, v70
	v_max_f32_e32 v71, 0, v71
	v_lshl_add_u64 v[74:75], v[64:65], 0, v[88:89]
	v_pk_mul_f32 v[70:71], v[70:71], v[70:71]
	v_pk_mul_f32 v[68:69], v[68:69], v[68:69]
	s_nop 0
	v_cvt_pk_bf16_f32 v64, v68, v69
	v_cvt_pk_bf16_f32 v65, v70, v71
	v_cvt_pk_bf16_f32 v66, v66, v67
	v_cvt_pk_bf16_f32 v67, v72, v73
	s_waitcnt lgkmcnt(0)
	global_store_dwordx4 v[220:221], v[212:215], off sc1
	ds_bpermute_b32 v216, v224, v64
	ds_bpermute_b32 v217, v224, v65
	ds_bpermute_b32 v218, v224, v66
	ds_bpermute_b32 v219, v224, v67
	v_lshl_add_u64 v[222:223], v[74:75], 0, v[226:227]
	ds_read2_b64 v[68:71], v207 offset0:128 offset1:144
	ds_read2_b64 v[64:67], v207 offset0:160 offset1:176
	v_lshl_add_u64 v[74:75], v[134:135], 0, s[10:11]
	v_lshl_add_u64 v[76:77], v[192:193], 0, v[74:75]
	s_mov_b64 s[10:11], 0x120000
	s_waitcnt lgkmcnt(1)
	v_pk_fma_f32 v[58:59], v[130:131], v[68:69], v[58:59] op_sel_hi:[1,0,1]
	v_pk_fma_f32 v[56:57], v[132:133], v[68:69], v[56:57] op_sel_hi:[1,0,1] neg_lo:[1,0,0] neg_hi:[1,0,0]
	v_pk_fma_f32 v[62:63], v[194:195], v[68:69], v[62:63] op_sel_hi:[1,0,1]
	v_pk_fma_f32 v[60:61], v[128:129], v[68:69], v[60:61] op_sel_hi:[1,0,1] neg_lo:[1,0,0] neg_hi:[1,0,0]
	v_pk_fma_f32 v[58:59], v[68:69], v[58:59], v[142:143] op_sel:[1,0,0]
	v_pk_fma_f32 v[56:57], v[68:69], v[56:57], v[140:141] op_sel:[1,0,0]
	v_pk_fma_f32 v[62:63], v[68:69], v[62:63], v[138:139] op_sel:[1,0,0]
	v_pk_fma_f32 v[60:61], v[68:69], v[60:61], v[136:137] op_sel:[1,0,0]
	v_max_f32_e32 v56, 0, v56
	v_max_f32_e32 v57, 0, v57
	v_max_f32_e32 v58, 0, v58
	v_max_f32_e32 v59, 0, v59
	v_pk_fma_f32 v[50:51], v[130:131], v[70:71], v[50:51] op_sel_hi:[1,0,1]
	v_pk_fma_f32 v[48:49], v[132:133], v[70:71], v[48:49] op_sel_hi:[1,0,1] neg_lo:[1,0,0] neg_hi:[1,0,0]
	v_max_f32_e32 v60, 0, v60
	v_max_f32_e32 v61, 0, v61
	v_max_f32_e32 v62, 0, v62
	v_max_f32_e32 v63, 0, v63
	v_pk_mul_f32 v[72:73], v[58:59], v[58:59]
	v_pk_mul_f32 v[58:59], v[56:57], v[56:57]
	v_pk_fma_f32 v[54:55], v[194:195], v[70:71], v[54:55] op_sel_hi:[1,0,1]
	v_pk_fma_f32 v[52:53], v[128:129], v[70:71], v[52:53] op_sel_hi:[1,0,1] neg_lo:[1,0,0] neg_hi:[1,0,0]
	v_pk_fma_f32 v[50:51], v[70:71], v[50:51], v[142:143] op_sel:[1,0,0]
	v_pk_fma_f32 v[48:49], v[70:71], v[48:49], v[140:141] op_sel:[1,0,0]
	v_pk_mul_f32 v[62:63], v[62:63], v[62:63]
	v_pk_mul_f32 v[60:61], v[60:61], v[60:61]
	v_pk_fma_f32 v[54:55], v[70:71], v[54:55], v[138:139] op_sel:[1,0,0]
	v_cvt_pk_bf16_f32 v56, v60, v61
	v_cvt_pk_bf16_f32 v57, v62, v63
	v_cvt_pk_bf16_f32 v58, v58, v59
	v_cvt_pk_bf16_f32 v59, v72, v73
	v_pk_fma_f32 v[52:53], v[70:71], v[52:53], v[136:137] op_sel:[1,0,0]
	v_max_f32_e32 v48, 0, v48
	v_max_f32_e32 v49, 0, v49
	v_max_f32_e32 v50, 0, v50
	v_max_f32_e32 v51, 0, v51
	s_waitcnt lgkmcnt(0)
	v_pk_fma_f32 v[42:43], v[130:131], v[64:65], v[42:43] op_sel_hi:[1,0,1]
	v_pk_fma_f32 v[40:41], v[132:133], v[64:65], v[40:41] op_sel_hi:[1,0,1] neg_lo:[1,0,0] neg_hi:[1,0,0]
	s_waitcnt lgkmcnt(0)
	global_store_dwordx4 v[222:223], v[216:219], off sc1
	ds_bpermute_b32 v212, v224, v56
	ds_bpermute_b32 v213, v224, v57
	ds_bpermute_b32 v214, v224, v58
	ds_bpermute_b32 v215, v224, v59
	v_lshl_add_u64 v[220:221], v[76:77], 0, v[226:227]
	v_max_f32_e32 v52, 0, v52
	v_max_f32_e32 v53, 0, v53
	v_max_f32_e32 v54, 0, v54
	v_max_f32_e32 v55, 0, v55
	v_pk_mul_f32 v[56:57], v[50:51], v[50:51]
	v_pk_mul_f32 v[50:51], v[48:49], v[48:49]
	v_lshl_add_u64 v[58:59], v[134:135], 0, s[10:11]
	v_pk_fma_f32 v[46:47], v[194:195], v[64:65], v[46:47] op_sel_hi:[1,0,1]
	v_pk_fma_f32 v[44:45], v[128:129], v[64:65], v[44:45] op_sel_hi:[1,0,1] neg_lo:[1,0,0] neg_hi:[1,0,0]
	v_pk_fma_f32 v[42:43], v[64:65], v[42:43], v[142:143] op_sel:[1,0,0]
	v_pk_fma_f32 v[40:41], v[64:65], v[40:41], v[140:141] op_sel:[1,0,0]
	v_pk_mul_f32 v[54:55], v[54:55], v[54:55]
	v_pk_mul_f32 v[52:53], v[52:53], v[52:53]
	v_lshl_add_u64 v[60:61], v[192:193], 0, v[58:59]
	v_cvt_pk_bf16_f32 v48, v52, v53
	v_cvt_pk_bf16_f32 v49, v54, v55
	v_cvt_pk_bf16_f32 v50, v50, v51
	v_cvt_pk_bf16_f32 v51, v56, v57
	v_pk_fma_f32 v[46:47], v[64:65], v[46:47], v[138:139] op_sel:[1,0,0]
	v_pk_fma_f32 v[44:45], v[64:65], v[44:45], v[136:137] op_sel:[1,0,0]
	v_max_f32_e32 v40, 0, v40
	v_max_f32_e32 v41, 0, v41
	v_max_f32_e32 v42, 0, v42
	v_max_f32_e32 v43, 0, v43
	s_mov_b64 s[10:11], 0x140000
	s_waitcnt lgkmcnt(0)
	global_store_dwordx4 v[220:221], v[212:215], off sc1
	ds_bpermute_b32 v216, v224, v48
	ds_bpermute_b32 v217, v224, v49
	ds_bpermute_b32 v218, v224, v50
	ds_bpermute_b32 v219, v224, v51
	v_lshl_add_u64 v[222:223], v[60:61], 0, v[226:227]
	v_max_f32_e32 v44, 0, v44
	v_max_f32_e32 v45, 0, v45
	v_max_f32_e32 v46, 0, v46
	v_max_f32_e32 v47, 0, v47
	v_pk_mul_f32 v[48:49], v[42:43], v[42:43]
	v_pk_mul_f32 v[42:43], v[40:41], v[40:41]
	v_lshl_add_u64 v[50:51], v[134:135], 0, s[10:11]
	v_pk_fma_f32 v[38:39], v[194:195], v[66:67], v[38:39] op_sel_hi:[1,0,1]
	v_pk_fma_f32 v[36:37], v[128:129], v[66:67], v[36:37] op_sel_hi:[1,0,1] neg_lo:[1,0,0] neg_hi:[1,0,0]
	v_pk_fma_f32 v[34:35], v[130:131], v[66:67], v[34:35] op_sel_hi:[1,0,1]
	v_pk_fma_f32 v[32:33], v[132:133], v[66:67], v[32:33] op_sel_hi:[1,0,1] neg_lo:[1,0,0] neg_hi:[1,0,0]
	v_pk_mul_f32 v[46:47], v[46:47], v[46:47]
	v_pk_mul_f32 v[44:45], v[44:45], v[44:45]
	v_lshl_add_u64 v[52:53], v[192:193], 0, v[50:51]
	v_cvt_pk_bf16_f32 v40, v44, v45
	v_cvt_pk_bf16_f32 v41, v46, v47
	v_cvt_pk_bf16_f32 v42, v42, v43
	v_cvt_pk_bf16_f32 v43, v48, v49
	v_pk_fma_f32 v[38:39], v[66:67], v[38:39], v[138:139] op_sel:[1,0,0]
	v_pk_fma_f32 v[36:37], v[66:67], v[36:37], v[136:137] op_sel:[1,0,0]
	v_pk_fma_f32 v[34:35], v[66:67], v[34:35], v[142:143] op_sel:[1,0,0]
	v_pk_fma_f32 v[32:33], v[66:67], v[32:33], v[140:141] op_sel:[1,0,0]
	s_mov_b64 s[10:11], 0x160000
	v_pk_fma_f32 v[26:27], v[92:93], v[68:69], v[26:27] op_sel_hi:[1,0,1]
	v_pk_fma_f32 v[24:25], v[112:113], v[68:69], v[24:25] op_sel_hi:[1,0,1] neg_lo:[1,0,0] neg_hi:[1,0,0]
	s_waitcnt lgkmcnt(0)
	global_store_dwordx4 v[222:223], v[216:219], off sc1
	ds_bpermute_b32 v212, v224, v40
	ds_bpermute_b32 v213, v224, v41
	ds_bpermute_b32 v214, v224, v42
	ds_bpermute_b32 v215, v224, v43
	v_lshl_add_u64 v[220:221], v[52:53], 0, v[226:227]
	v_max_f32_e32 v36, 0, v36
	v_max_f32_e32 v37, 0, v37
	v_max_f32_e32 v38, 0, v38
	v_max_f32_e32 v39, 0, v39
	v_max_f32_e32 v32, 0, v32
	v_max_f32_e32 v33, 0, v33
	v_max_f32_e32 v34, 0, v34
	v_max_f32_e32 v35, 0, v35
	v_lshl_add_u64 v[42:43], v[134:135], 0, s[10:11]
	v_pk_fma_f32 v[30:31], v[96:97], v[68:69], v[30:31] op_sel_hi:[1,0,1]
	v_pk_fma_f32 v[28:29], v[120:121], v[68:69], v[28:29] op_sel_hi:[1,0,1] neg_lo:[1,0,0] neg_hi:[1,0,0]
	v_pk_fma_f32 v[26:27], v[68:69], v[26:27], v[118:119] op_sel:[1,0,0]
	v_pk_fma_f32 v[24:25], v[68:69], v[24:25], v[116:117] op_sel:[1,0,0]
	v_pk_mul_f32 v[38:39], v[38:39], v[38:39]
	v_pk_mul_f32 v[36:37], v[36:37], v[36:37]
	v_pk_mul_f32 v[40:41], v[34:35], v[34:35]
	v_pk_mul_f32 v[34:35], v[32:33], v[32:33]
	v_lshl_add_u64 v[44:45], v[192:193], 0, v[42:43]
	v_cvt_pk_bf16_f32 v32, v36, v37
	v_cvt_pk_bf16_f32 v33, v38, v39
	v_pk_fma_f32 v[30:31], v[68:69], v[30:31], v[126:127] op_sel:[1,0,0]
	v_pk_fma_f32 v[28:29], v[68:69], v[28:29], v[124:125] op_sel:[1,0,0]
	v_max_f32_e32 v24, 0, v24
	v_max_f32_e32 v25, 0, v25
	v_max_f32_e32 v26, 0, v26
	v_max_f32_e32 v27, 0, v27
	v_pk_fma_f32 v[18:19], v[92:93], v[70:71], v[18:19] op_sel_hi:[1,0,1]
	v_pk_fma_f32 v[16:17], v[112:113], v[70:71], v[16:17] op_sel_hi:[1,0,1] neg_lo:[1,0,0] neg_hi:[1,0,0]
	v_cvt_pk_bf16_f32 v34, v34, v35
	v_cvt_pk_bf16_f32 v35, v40, v41
	s_waitcnt lgkmcnt(0)
	global_store_dwordx4 v[220:221], v[212:215], off sc1
	ds_bpermute_b32 v216, v224, v32
	ds_bpermute_b32 v217, v224, v33
	ds_bpermute_b32 v218, v224, v34
	ds_bpermute_b32 v219, v224, v35
	v_lshl_add_u64 v[222:223], v[44:45], 0, v[226:227]
	v_max_f32_e32 v28, 0, v28
	v_max_f32_e32 v29, 0, v29
	v_max_f32_e32 v30, 0, v30
	v_max_f32_e32 v31, 0, v31
	v_pk_mul_f32 v[32:33], v[26:27], v[26:27]
	v_pk_mul_f32 v[26:27], v[24:25], v[24:25]
	v_lshl_add_u64 v[24:25], s[46:47], 0, v[74:75]
	v_pk_fma_f32 v[22:23], v[96:97], v[70:71], v[22:23] op_sel_hi:[1,0,1]
	v_pk_fma_f32 v[20:21], v[120:121], v[70:71], v[20:21] op_sel_hi:[1,0,1] neg_lo:[1,0,0] neg_hi:[1,0,0]
	v_pk_fma_f32 v[18:19], v[70:71], v[18:19], v[118:119] op_sel:[1,0,0]
	v_pk_fma_f32 v[16:17], v[70:71], v[16:17], v[116:117] op_sel:[1,0,0]
	v_pk_mul_f32 v[30:31], v[30:31], v[30:31]
	v_pk_mul_f32 v[28:29], v[28:29], v[28:29]
	v_lshl_add_u64 v[34:35], v[24:25], 0, v[88:89]
	v_cvt_pk_bf16_f32 v24, v28, v29
	v_cvt_pk_bf16_f32 v25, v30, v31
	v_pk_fma_f32 v[22:23], v[70:71], v[22:23], v[126:127] op_sel:[1,0,0]
	v_pk_fma_f32 v[20:21], v[70:71], v[20:21], v[124:125] op_sel:[1,0,0]
	v_max_f32_e32 v16, 0, v16
	v_max_f32_e32 v17, 0, v17
	v_max_f32_e32 v18, 0, v18
	v_max_f32_e32 v19, 0, v19
	v_pk_fma_f32 v[10:11], v[92:93], v[64:65], v[10:11] op_sel_hi:[1,0,1]
	v_pk_fma_f32 v[8:9], v[112:113], v[64:65], v[8:9] op_sel_hi:[1,0,1] neg_lo:[1,0,0] neg_hi:[1,0,0]
	v_cvt_pk_bf16_f32 v26, v26, v27
	v_cvt_pk_bf16_f32 v27, v32, v33
	s_waitcnt lgkmcnt(0)
	global_store_dwordx4 v[222:223], v[216:219], off sc1
	ds_bpermute_b32 v212, v224, v24
	ds_bpermute_b32 v213, v224, v25
	ds_bpermute_b32 v214, v224, v26
	ds_bpermute_b32 v215, v224, v27
	v_lshl_add_u64 v[220:221], v[34:35], 0, v[226:227]
	v_max_f32_e32 v20, 0, v20
	v_max_f32_e32 v21, 0, v21
	v_max_f32_e32 v22, 0, v22
	v_max_f32_e32 v23, 0, v23
	v_pk_mul_f32 v[24:25], v[18:19], v[18:19]
	v_pk_mul_f32 v[18:19], v[16:17], v[16:17]
	v_lshl_add_u64 v[16:17], s[46:47], 0, v[58:59]
	v_pk_fma_f32 v[14:15], v[96:97], v[64:65], v[14:15] op_sel_hi:[1,0,1]
	v_pk_fma_f32 v[12:13], v[120:121], v[64:65], v[12:13] op_sel_hi:[1,0,1] neg_lo:[1,0,0] neg_hi:[1,0,0]
	v_pk_fma_f32 v[10:11], v[64:65], v[10:11], v[118:119] op_sel:[1,0,0]
	v_pk_fma_f32 v[8:9], v[64:65], v[8:9], v[116:117] op_sel:[1,0,0]
	v_pk_mul_f32 v[22:23], v[22:23], v[22:23]
	v_pk_mul_f32 v[20:21], v[20:21], v[20:21]
	v_lshl_add_u64 v[26:27], v[16:17], 0, v[88:89]
	v_cvt_pk_bf16_f32 v16, v20, v21
	v_cvt_pk_bf16_f32 v17, v22, v23
	v_pk_fma_f32 v[14:15], v[64:65], v[14:15], v[126:127] op_sel:[1,0,0]
	v_pk_fma_f32 v[12:13], v[64:65], v[12:13], v[124:125] op_sel:[1,0,0]
	v_max_f32_e32 v8, 0, v8
	v_max_f32_e32 v9, 0, v9
	v_max_f32_e32 v10, 0, v10
	v_max_f32_e32 v11, 0, v11
	v_pk_fma_f32 v[2:3], v[92:93], v[66:67], v[2:3] op_sel_hi:[1,0,1]
	v_pk_fma_f32 v[0:1], v[112:113], v[66:67], v[0:1] op_sel_hi:[1,0,1] neg_lo:[1,0,0] neg_hi:[1,0,0]
	v_cvt_pk_bf16_f32 v18, v18, v19
	v_cvt_pk_bf16_f32 v19, v24, v25
	s_waitcnt lgkmcnt(0)
	global_store_dwordx4 v[220:221], v[212:215], off sc1
	ds_bpermute_b32 v216, v224, v16
	ds_bpermute_b32 v217, v224, v17
	ds_bpermute_b32 v218, v224, v18
	ds_bpermute_b32 v219, v224, v19
	v_lshl_add_u64 v[222:223], v[26:27], 0, v[226:227]
	v_max_f32_e32 v12, 0, v12
	v_max_f32_e32 v13, 0, v13
	v_max_f32_e32 v14, 0, v14
	v_max_f32_e32 v15, 0, v15
	v_pk_mul_f32 v[16:17], v[10:11], v[10:11]
	v_pk_mul_f32 v[10:11], v[8:9], v[8:9]
	v_lshl_add_u64 v[8:9], s[46:47], 0, v[50:51]
	v_pk_fma_f32 v[2:3], v[66:67], v[2:3], v[118:119] op_sel:[1,0,0]
	v_pk_fma_f32 v[0:1], v[66:67], v[0:1], v[116:117] op_sel:[1,0,0]
	v_pk_mul_f32 v[14:15], v[14:15], v[14:15]
	v_pk_mul_f32 v[12:13], v[12:13], v[12:13]
	v_lshl_add_u64 v[18:19], v[8:9], 0, v[88:89]
	v_cvt_pk_bf16_f32 v8, v12, v13
	v_cvt_pk_bf16_f32 v9, v14, v15
	v_pk_fma_f32 v[6:7], v[96:97], v[66:67], v[6:7] op_sel_hi:[1,0,1]
	v_pk_fma_f32 v[4:5], v[120:121], v[66:67], v[4:5] op_sel_hi:[1,0,1] neg_lo:[1,0,0] neg_hi:[1,0,0]
	v_max_f32_e32 v0, 0, v0
	v_max_f32_e32 v1, 0, v1
	v_max_f32_e32 v2, 0, v2
	v_max_f32_e32 v3, 0, v3
	v_cvt_pk_bf16_f32 v10, v10, v11
	v_cvt_pk_bf16_f32 v11, v16, v17
	s_waitcnt lgkmcnt(0)
	global_store_dwordx4 v[222:223], v[216:219], off sc1
	ds_bpermute_b32 v212, v224, v8
	ds_bpermute_b32 v213, v224, v9
	ds_bpermute_b32 v214, v224, v10
	ds_bpermute_b32 v215, v224, v11
	v_lshl_add_u64 v[220:221], v[18:19], 0, v[226:227]
	v_pk_fma_f32 v[6:7], v[66:67], v[6:7], v[126:127] op_sel:[1,0,0]
	v_pk_fma_f32 v[4:5], v[66:67], v[4:5], v[124:125] op_sel:[1,0,0]
	v_pk_mul_f32 v[8:9], v[2:3], v[2:3]
	v_pk_mul_f32 v[2:3], v[0:1], v[0:1]
	v_lshl_add_u64 v[0:1], s[46:47], 0, v[42:43]
	v_max_f32_e32 v4, 0, v4
	v_max_f32_e32 v5, 0, v5
	v_max_f32_e32 v6, 0, v6
	v_max_f32_e32 v7, 0, v7
	v_lshl_add_u64 v[10:11], v[0:1], 0, v[88:89]
	s_mov_b64 s[10:11], s[42:43]
	v_pk_mul_f32 v[6:7], v[6:7], v[6:7]
	v_pk_mul_f32 v[4:5], v[4:5], v[4:5]
	s_nop 0
	v_cvt_pk_bf16_f32 v0, v4, v5
	v_cvt_pk_bf16_f32 v1, v6, v7
	v_cvt_pk_bf16_f32 v2, v2, v3
	v_cvt_pk_bf16_f32 v3, v8, v9
	s_waitcnt lgkmcnt(0)
	global_store_dwordx4 v[220:221], v[212:215], off sc1
	ds_bpermute_b32 v216, v224, v0
	ds_bpermute_b32 v217, v224, v1
	ds_bpermute_b32 v218, v224, v2
	ds_bpermute_b32 v219, v224, v3
	v_lshl_add_u64 v[222:223], v[10:11], 0, v[226:227]
	s_waitcnt lgkmcnt(0)
	global_store_dwordx4 v[222:223], v[216:219], off sc1
	s_cbranch_vccz .LBB0_1256
	s_waitcnt vmcnt(0)
	s_cmpk_gt_u32 s4, 0xff
	s_cbranch_scc1 .LBB0_1267
	s_barrier
